# k52 + POST: 9 pk_mul+s_nop pairs replaced by plain f32 multiplies (same rounding, fewer wait states)
# speedup vs baseline: 1.0034x; 1.0018x over previous
; #define LAS __attribute__((address_space(3)))
; DI unsigned pk2(float lo, float hi) { f32x2 x = {lo, hi}; return __builtin_bit_cast(unsigned, __builtin_convertvector(x, bf16x2_t)); }
; DI float sum32(float v) { v += __shfl_xor(v, 16); return sum16(v); }
; DI f32x2 unpk(unsigned w) { f32x2 r = {bflo(w), bfhi(w)}; return r; }
; template <int HP> DI void rope2(f32x2& x, int hl, const LAS f32x2* cs) {
;   const float pa = __shfl_xor(x[0], HP), pb = __shfl_xor(x[1], HP);
;   if (hl < HP) { const f32x2 c0 = cs[2 * hl], c1 = cs[2 * hl + 1]; x[0] = x[0] * c0[0] - pa * c0[1]; x[1] = x[1] * c1[0] - pb * c1[1]; }
;   else if (hl < 2 * HP) { const f32x2 c0 = cs[2 * (hl - HP)], c1 = cs[2 * (hl - HP) + 1]; x[0] = x[0] * c0[0] + pa * c0[1]; x[1] = x[1] * c1[0] + pb * c1[1]; }
; }
; DI void post_unit(const Params& p, int l, int unit, LAS unsigned char* lds) {
;     ...
;   for (int tp = 0; tp < 4; ++tp) {
;     constexpr int segcol[16] = {C_QA, C_QA + 128, C_KA, C_QI, C_QI + 128, C_QI + 256, C_QI + 384, C_KI, C_QB, C_QB + 128, C_KB, C_KB + 128, C_QC, C_QC + 128, C_KC, C_KC + 128};
;     unsigned raw2[2][16];
; #pragma unroll
;     for (int hf = 0; hf < 2; ++hf) { const u16* rowl = proj + (tok0 + w * 8 + 2 * tp + hf) * NP;
; #pragma unroll
;       for (int s = 0; s < 16; ++s) raw2[hf][s] = *(const unsigned*)(rowl + segcol[s] + 2 * lane); }
; #pragma unroll
;     for (int hf = 0; hf < 2; ++hf) {
;     const int t = w * 8 + 2 * tp + hf; u16* row = proj + (tok0 + t) * NP;
; #pragma unroll
;     for (int s = 0; s < 16; ++s) {
;       f32x2 x = unpk(raw2[hf][s]); u16* pp = row + segcol[s] + 2 * lane;
;       if (s < 2) {
;         const float rs = rsqrtf(sum32(x[0] * x[0] + x[1] * x[1]) * (1.0f / 64.0f) + EPS);
;         x[0] *= rs * qna[2 * hl]; x[1] *= rs * qna[2 * hl + 1]; rope2<4>(x, hl, cs16 + t * 8);
;         x *= LOG2E * 0.125f; *(unsigned*)pp = pk2(x[0], x[1]);
.LBB0_150:
	ds_read_b128 v[208:211], v35
	ds_read_b128 v[212:215], v35 offset:64
	ds_read_b128 v[216:219], v39
	ds_read_b128 v[220:223], v39 offset:256
	ds_read_b128 v[224:227], v40
	ds_read_b128 v[228:231], v40 offset:32
	ds_read_b128 v[232:235], v35 offset:128
	ds_read_b128 v[236:239], v39 offset:512
	ds_read_b128 v[240:243], v40 offset:64
	s_waitcnt lgkmcnt(0)
	s_orn2_b64 s[98:99], s[14:15], s[12:13]
	s_orn2_b64 s[100:101], s[8:9], s[6:7]
	v_cndmask_b32_e64 v80, v212, v208, s[12:13]
	v_cndmask_b32_e64 v80, 1.0, v80, s[98:99]
	v_cndmask_b32_e64 v81, v214, v210, s[12:13]
	v_cndmask_b32_e64 v81, 1.0, v81, s[98:99]
	v_cndmask_b32_e64 v82, -v213, v209, s[12:13]
	v_cndmask_b32_e64 v82, 0, v82, s[98:99]
	v_cndmask_b32_e64 v83, -v215, v211, s[12:13]
	v_cndmask_b32_e64 v83, 0, v83, s[98:99]
	v_cndmask_b32_e64 v84, v220, v216, s[10:11]
	v_cndmask_b32_e64 v85, v222, v218, s[10:11]
	v_cndmask_b32_e64 v86, -v221, v217, s[10:11]
	v_cndmask_b32_e64 v87, -v223, v219, s[10:11]
	v_cndmask_b32_e64 v88, v228, v224, s[6:7]
	v_cndmask_b32_e64 v88, 1.0, v88, s[100:101]
	v_cndmask_b32_e64 v89, v230, v226, s[6:7]
	v_cndmask_b32_e64 v89, 1.0, v89, s[100:101]
	v_cndmask_b32_e64 v90, -v229, v225, s[6:7]
	v_cndmask_b32_e64 v90, 0, v90, s[100:101]
	v_cndmask_b32_e64 v91, -v231, v227, s[6:7]
	v_cndmask_b32_e64 v91, 0, v91, s[100:101]
	v_cndmask_b32_e64 v92, v232, v212, s[12:13]
	v_cndmask_b32_e64 v92, 1.0, v92, s[98:99]
	v_cndmask_b32_e64 v93, v234, v214, s[12:13]
	v_cndmask_b32_e64 v93, 1.0, v93, s[98:99]
	v_cndmask_b32_e64 v94, -v233, v213, s[12:13]
	v_cndmask_b32_e64 v94, 0, v94, s[98:99]
	v_cndmask_b32_e64 v95, -v235, v215, s[12:13]
	v_cndmask_b32_e64 v95, 0, v95, s[98:99]
	v_cndmask_b32_e64 v96, v240, v228, s[6:7]
	v_cndmask_b32_e64 v96, 1.0, v96, s[100:101]
	v_cndmask_b32_e64 v97, v242, v230, s[6:7]
	v_cndmask_b32_e64 v97, 1.0, v97, s[100:101]
	v_cndmask_b32_e64 v98, -v241, v229, s[6:7]
	v_cndmask_b32_e64 v98, 0, v98, s[100:101]
	v_cndmask_b32_e64 v99, -v243, v231, s[6:7]
	v_cndmask_b32_e64 v99, 0, v99, s[100:101]
	v_lshl_add_u64 v[18:19], v[12:13], 0, v[0:1]
	v_add_co_u32_e32 v20, vcc, 0xa000000, v18
	s_mov_b32 s2, 0xa001000
	v_addc_co_u32_e32 v21, vcc, 0, v19, vcc
	global_load_dword v49, v[20:21], off
	v_add_co_u32_e32 v22, vcc, s2, v18
	s_mov_b32 s2, 0xa003000
	s_nop 0
	v_addc_co_u32_e32 v23, vcc, 0, v19, vcc
	v_add_co_u32_e32 v42, vcc, s77, v18
	global_load_dword v59, v[20:21], off offset:512
	global_load_dword v70, v[20:21], off offset:768
	global_load_dword v69, v[20:21], off offset:1024
	global_load_dword v68, v[20:21], off offset:1280
	global_load_dword v67, v[20:21], off offset:1536
	global_load_dword v58, v[20:21], off offset:1792
	global_load_dword v71, v[20:21], off offset:256
	v_addc_co_u32_e32 v43, vcc, 0, v19, vcc
	global_load_dword v56, v[20:21], off offset:2432
	global_load_dword v66, v[20:21], off offset:2688
	global_load_dword v65, v[20:21], off offset:2944
	global_load_dword v64, v[20:21], off offset:3200
	global_load_dword v54, v[22:23], off offset:384
	global_load_dword v63, v[22:23], off offset:640
	global_load_dword v62, v[22:23], off offset:896
	global_load_dword v61, v[22:23], off offset:1152
	v_add_co_u32_e32 v20, vcc, s2, v18
	global_load_dword v60, v[42:43], off offset:512
	global_load_dword v57, v[42:43], off offset:768
	global_load_dword v55, v[42:43], off offset:1024
	global_load_dword v53, v[42:43], off offset:1280
	global_load_dword v52, v[42:43], off offset:1536
	global_load_dword v51, v[42:43], off offset:1792
	global_load_dword v50, v[42:43], off offset:2048
	global_load_dword v48, v[42:43], off offset:2304
	v_addc_co_u32_e32 v21, vcc, 0, v19, vcc
	global_load_dword v47, v[42:43], off offset:2944
	global_load_dword v46, v[42:43], off offset:3200
	global_load_dword v45, v[42:43], off offset:3456
	global_load_dword v44, v[42:43], off offset:3712
	s_nop 0
	global_load_dword v43, v[20:21], off offset:896
	global_load_dword v42, v[20:21], off offset:1152
	global_load_dword v41, v[20:21], off offset:1408
	global_load_dword v3, v[20:21], off offset:1664
	s_waitcnt vmcnt(31)
	v_and_b32_e32 v21, 0xffff0000, v49
	v_lshlrev_b32_e32 v20, 16, v49
	v_mul_f32_e32 v22, v20, v20
	v_fmac_f32_e32 v22, v21, v21
	v_mov_b32_e32 v23, v22
	s_nop 1
	v_permlane16_swap_b32_e32 v22, v23
	v_add_f32_e32 v22, v22, v23
	s_nop 1
	v_add_f32_dpp v22, v22, v22 row_ror:8 row_mask:0xf bank_mask:0xf
	s_nop 1
	v_add_f32_dpp v22, v22, v22 row_ror:4 row_mask:0xf bank_mask:0xf
	s_nop 1
	v_add_f32_dpp v22, v22, v22 quad_perm:[2,3,0,1] row_mask:0xf bank_mask:0xf
	s_nop 1
	v_add_f32_dpp v22, v22, v22 quad_perm:[1,0,3,2] row_mask:0xf bank_mask:0xf
	v_fmamk_f32 v22, v22, 0x3c800000, v170
	v_rsq_f32_e32 v22, v22
	s_nop 0
	v_mul_f32_e32 v23, v5, v22
	v_mul_f32_e32 v22, v4, v22
	v_mul_f32_e32 v22, v22, v20
	v_mul_f32_e32 v23, v23, v21
	ds_bpermute_b32 v20, v28, v22
	ds_bpermute_b32 v21, v28, v23
	v_add_u32_e32 v49, 0, v35
	s_waitcnt lgkmcnt(0)
; #define LAS __attribute__((address_space(3)))
; DI unsigned pk2(float lo, float hi) { f32x2 x = {lo, hi}; return __builtin_bit_cast(unsigned, __builtin_convertvector(x, bf16x2_t)); }
; DI float sum32(float v) { v += __shfl_xor(v, 16); return sum16(v); }
; DI float sum64(float v) { v += __shfl_xor(v, 32); return sum32(v); }
; DI f32x2 unpk(unsigned w) { f32x2 r = {bflo(w), bfhi(w)}; return r; }
; DI void post_unit(const Params& p, int l, int unit, LAS unsigned char* lds) {
;     ...
;     for (int s = 0; s < 16; ++s) {
;       f32x2 x = unpk(raw2[hf][s]); u16* pp = row + segcol[s] + 2 * lane;
;       if (s < 2) {
;         const float rs = rsqrtf(sum32(x[0] * x[0] + x[1] * x[1]) * (1.0f / 64.0f) + EPS);
;         x[0] *= rs * qna[2 * hl]; x[1] *= rs * qna[2 * hl + 1]; rope2<4>(x, hl, cs16 + t * 8);
;         x *= LOG2E * 0.125f; *(unsigned*)pp = pk2(x[0], x[1]);
;       } else if (s == 2) {
;         const float rs = rsqrtf(sum64(x[0] * x[0] + x[1] * x[1]) * (1.0f / 128.0f) + EPS);
;         *(LAS unsigned*)(At + t * 272 + lane * 4) = pk2(x[0] * rs, x[1] * rs);
;       } else if (s < 7) {
;         rope2<4>(x, hl, cs16 + t * 8); *(unsigned*)pp = pk2(x[0], x[1]);
;       } else if (s == 7) {
;         const float rs = rsqrtf(sum32(x[0] * x[0] + x[1] * x[1]) * (1.0f / 64.0f) + EPS);
;         x *= rs; rope2<4>(x, hl, cs16 + t * 8); if (lane < 32) *(unsigned*)((u16*)(p.ws + WS_KIC) + (tok0 + t) * 64 + 2 * lane) = pk2(x[0], x[1]);
	v_mul_f32_e32 v22, v80, v22
	v_mul_f32_e32 v23, v81, v23
	v_fmac_f32_e32 v22, v82, v20
	v_fmac_f32_e32 v23, v83, v21
	s_mov_b64 s[2:3], 0xa000000
	v_lshl_add_u64 v[20:21], v[18:19], 0, s[2:3]
	s_mov_b32 s2, 0x3e38aa3b
	v_mul_f32_e32 v22, s2, v22
	v_mul_f32_e32 v23, s2, v23
	v_cvt_pk_bf16_f32 v22, v22, v23
	global_store_dword v[20:21], v22, off
	s_waitcnt vmcnt(25)
	v_and_b32_e32 v21, 0xffff0000, v71
	v_lshlrev_b32_e32 v20, 16, v71
	v_mul_f32_e32 v22, v20, v20
	v_fmac_f32_e32 v22, v21, v21
	v_mov_b32_e32 v23, v22
	s_nop 1
	v_permlane16_swap_b32_e32 v22, v23
	v_add_f32_e32 v22, v22, v23
	s_nop 1
	v_add_f32_dpp v22, v22, v22 row_ror:8 row_mask:0xf bank_mask:0xf
	s_nop 1
	v_add_f32_dpp v22, v22, v22 row_ror:4 row_mask:0xf bank_mask:0xf
	s_nop 1
	v_add_f32_dpp v22, v22, v22 quad_perm:[2,3,0,1] row_mask:0xf bank_mask:0xf
	s_nop 1
	v_add_f32_dpp v22, v22, v22 quad_perm:[1,0,3,2] row_mask:0xf bank_mask:0xf
	v_fmamk_f32 v22, v22, 0x3c800000, v170
	v_rsq_f32_e32 v22, v22
	s_nop 0
	v_mul_f32_e32 v23, v5, v22
	v_mul_f32_e32 v22, v4, v22
	v_mul_f32_e32 v22, v22, v20
	v_mul_f32_e32 v23, v23, v21
	ds_bpermute_b32 v20, v28, v22
	ds_bpermute_b32 v21, v28, v23
	s_waitcnt lgkmcnt(0)
	v_mul_f32_e32 v22, v80, v22
	v_mul_f32_e32 v23, v81, v23
	v_fmac_f32_e32 v22, v82, v20
	v_fmac_f32_e32 v23, v83, v21
	s_mov_b64 s[2:3], 0xa000100
	v_lshl_add_u64 v[20:21], v[18:19], 0, s[2:3]
	s_mov_b32 s2, 0x3e38aa3b
	v_mul_f32_e32 v22, s2, v22
	v_mul_f32_e32 v23, s2, v23
	v_cvt_pk_bf16_f32 v22, v22, v23
	global_store_dword v[20:21], v22, off
	v_lshlrev_b32_e32 v20, 16, v59
	v_and_b32_e32 v21, 0xffff0000, v59
	v_pk_mul_f32 v[22:23], v[20:21], v[20:21]
	v_add_u32_e32 v59, 0, v33
	v_add_f32_e32 v22, v22, v23
	v_mov_b32_e32 v23, v22
	s_nop 1
	v_permlane32_swap_b32_e32 v22, v23
	v_add_f32_e32 v22, v22, v23
	v_mov_b32_e32 v23, v22
	s_nop 1
	v_permlane16_swap_b32_e32 v22, v23
	v_add_f32_e32 v22, v22, v23
	s_nop 1
	v_add_f32_dpp v22, v22, v22 row_ror:8 row_mask:0xf bank_mask:0xf
	s_nop 1
	v_add_f32_dpp v22, v22, v22 row_ror:4 row_mask:0xf bank_mask:0xf
	s_nop 1
	v_add_f32_dpp v22, v22, v22 quad_perm:[2,3,0,1] row_mask:0xf bank_mask:0xf
	s_nop 1
	v_add_f32_dpp v22, v22, v22 quad_perm:[1,0,3,2] row_mask:0xf bank_mask:0xf
	v_fmamk_f32 v22, v22, 0x3c000000, v170
	v_rsq_f32_e32 v22, v22
	s_nop 0
	v_pk_mul_f32 v[20:21], v[22:23], v[20:21] op_sel_hi:[0,1]
	v_cvt_pk_bf16_f32 v20, v20, v21
	ds_write_b32 v59, v20
	v_lshlrev_b32_e32 v20, 16, v70
	v_and_b32_e32 v21, 0xffff0000, v70
	ds_bpermute_b32 v70, v28, v20
	ds_bpermute_b32 v23, v28, v21
	s_waitcnt lgkmcnt(0)
	v_mul_f32_e32 v20, v80, v20
	v_mul_f32_e32 v21, v81, v21
	v_fmac_f32_e32 v20, v82, v70
	v_fmac_f32_e32 v21, v83, v23
	s_mov_b64 s[2:3], 0xa000300
	v_lshl_add_u64 v[22:23], v[18:19], 0, s[2:3]
	v_cvt_pk_bf16_f32 v20, v20, v21
	global_store_dword v[22:23], v20, off
	v_lshlrev_b32_e32 v20, 16, v69
	v_and_b32_e32 v21, 0xffff0000, v69
	ds_bpermute_b32 v69, v28, v20
	ds_bpermute_b32 v23, v28, v21
	s_waitcnt lgkmcnt(0)
	v_mul_f32_e32 v20, v80, v20
	v_mul_f32_e32 v21, v81, v21
	v_fmac_f32_e32 v20, v82, v69
	v_fmac_f32_e32 v21, v83, v23
	s_mov_b64 s[2:3], 0xa000400
	v_lshl_add_u64 v[22:23], v[18:19], 0, s[2:3]
	v_cvt_pk_bf16_f32 v20, v20, v21
	global_store_dword v[22:23], v20, off
	v_lshlrev_b32_e32 v20, 16, v68
	v_and_b32_e32 v21, 0xffff0000, v68
	ds_bpermute_b32 v68, v28, v20
	ds_bpermute_b32 v23, v28, v21
	s_waitcnt lgkmcnt(0)
	v_mul_f32_e32 v20, v80, v20
	v_mul_f32_e32 v21, v81, v21
	v_fmac_f32_e32 v20, v82, v68
	v_fmac_f32_e32 v21, v83, v23
	s_mov_b64 s[2:3], 0xa000500
	v_lshl_add_u64 v[22:23], v[18:19], 0, s[2:3]
	v_cvt_pk_bf16_f32 v20, v20, v21
	global_store_dword v[22:23], v20, off
	v_lshlrev_b32_e32 v20, 16, v67
	v_and_b32_e32 v21, 0xffff0000, v67
	ds_bpermute_b32 v67, v28, v20
	ds_bpermute_b32 v23, v28, v21
	s_waitcnt lgkmcnt(0)
	v_mul_f32_e32 v20, v80, v20
	v_mul_f32_e32 v21, v81, v21
	v_fmac_f32_e32 v20, v82, v67
	v_fmac_f32_e32 v21, v83, v23
	s_mov_b64 s[2:3], 0xa000600
	v_lshl_add_u64 v[22:23], v[18:19], 0, s[2:3]
	v_cvt_pk_bf16_f32 v20, v20, v21
	global_store_dword v[22:23], v20, off
	v_lshlrev_b32_e32 v20, 16, v58
	v_and_b32_e32 v21, 0xffff0000, v58
	v_mul_f32_e32 v22, v20, v20
	v_fmac_f32_e32 v22, v21, v21
	v_mov_b32_e32 v23, v22
	s_nop 1
	v_permlane16_swap_b32_e32 v22, v23
	v_add_f32_e32 v22, v22, v23
	s_nop 1
	v_add_f32_dpp v22, v22, v22 row_ror:8 row_mask:0xf bank_mask:0xf
	s_nop 1
	v_add_f32_dpp v22, v22, v22 row_ror:4 row_mask:0xf bank_mask:0xf
	s_nop 1
	v_add_f32_dpp v22, v22, v22 quad_perm:[2,3,0,1] row_mask:0xf bank_mask:0xf
	s_nop 1
	v_add_f32_dpp v22, v22, v22 quad_perm:[1,0,3,2] row_mask:0xf bank_mask:0xf
	v_fmamk_f32 v22, v22, 0x3c800000, v170
	v_rsq_f32_e32 v22, v22
	s_nop 0
	v_pk_mul_f32 v[20:21], v[22:23], v[20:21] op_sel_hi:[0,1]
	ds_bpermute_b32 v22, v28, v20
	ds_bpermute_b32 v23, v28, v21
	s_and_saveexec_b64 s[2:3], s[12:13]
	s_xor_b64 s[18:19], exec, s[2:3]
	s_cbranch_execz .LBB0_314
	s_and_saveexec_b64 s[30:31], s[14:15]
	s_cbranch_execz .LBB0_189
	s_waitcnt lgkmcnt(0)
	v_mul_f32_e32 v20, v20, v208
	v_mul_f32_e32 v21, v210, v21
	v_fmac_f32_e32 v20, v209, v22
	v_fmac_f32_e32 v21, v211, v23

; DI unsigned pk2(float lo, float hi) { f32x2 x = {lo, hi}; return __builtin_bit_cast(unsigned, __builtin_convertvector(x, bf16x2_t)); }
; DI float sum16(float v) { v += __shfl_xor(v, 8); v += __shfl_xor(v, 4); v += __shfl_xor(v, 2); v += __shfl_xor(v, 1); return v; }
; DI void post_unit(const Params& p, int l, int unit, LAS unsigned char* lds) {
;     ...
;       } else if (s < 12) {
;         rope2<16>(x, hl, cs64 + t * 32);
;         const int hd = ((s & 1) ? 2 : 0) + hsel;
;         const float lg = log1pf(-exp2f(-5.0f - (float)hd));
;         const float f = (s < 10) ? expf(lg * (float)(t + 1)) : expf(lg * (float)(63 - t)) * 0.125f;
;         x *= f; *(unsigned*)pp = pk2(x[0], x[1]);
;       } else {
;         const float* gn = (s < 14) ? qnc : knc;
;         const float rs = rsqrtf(sum16(x[0] * x[0] + x[1] * x[1]) * (1.0f / 32.0f) + EPS);
;         x[0] *= rs * gn[2 * hl16]; x[1] *= rs * gn[2 * hl16 + 1]; rope2<2>(x, hl16, cs8 + t * 4);
;         if (s < 14) x *= LOG2E * 0.17677669529663687f;
;         *(unsigned*)pp = pk2(x[0], x[1]);
.LBB0_196:
	s_or_b64 exec, exec, s[18:19]
	v_add_u32_e32 v58, s36, v2
	s_waitcnt lgkmcnt(1)
	v_add_u32_e32 v67, 1, v58
	v_cvt_f32_i32_e32 v67, v67
	s_mov_b64 s[2:3], 0xa000980
	s_waitcnt lgkmcnt(0)
	v_lshl_add_u64 v[22:23], v[18:19], 0, s[2:3]
	v_mul_f32_e32 v68, v31, v67
	v_mul_f32_e32 v69, 0x3fb8aa3b, v68
	v_fma_f32 v70, v68, s64, -v69
	v_rndne_f32_e32 v71, v69
	v_fmac_f32_e32 v70, 0x32a5705f, v68
	v_sub_f32_e32 v69, v69, v71
	v_add_f32_e32 v69, v69, v70
	v_exp_f32_e32 v69, v69
	v_cvt_i32_f32_e32 v70, v71
	v_cmp_ngt_f32_e32 vcc, s65, v68
	v_ldexp_f32 v69, v69, v70
	s_nop 0
	v_cndmask_b32_e32 v69, 0, v69, vcc
	v_cmp_nlt_f32_e32 vcc, s89, v68
	s_nop 1
	v_cndmask_b32_e32 v68, v177, v69, vcc
	v_pk_mul_f32 v[20:21], v[68:69], v[20:21] op_sel_hi:[0,1]
	v_cvt_pk_bf16_f32 v20, v20, v21
	global_store_dword v[22:23], v20, off
	s_waitcnt vmcnt(29)
	v_lshlrev_b32_e32 v68, 16, v66
	v_and_b32_e32 v20, 0xffff0000, v66
	ds_bpermute_b32 v66, v26, v68
	ds_bpermute_b32 v21, v26, v20
	s_waitcnt lgkmcnt(0)
	v_mul_f32_e32 v22, v84, v68
	v_mul_f32_e32 v23, v85, v20
	v_fmac_f32_e32 v22, v86, v66
	v_fmac_f32_e32 v23, v87, v21
	s_waitcnt lgkmcnt(1)
	v_mul_f32_e32 v66, v32, v67
	v_mul_f32_e32 v67, 0x3fb8aa3b, v66
	v_fma_f32 v68, v66, s64, -v67
	v_rndne_f32_e32 v69, v67
	v_fmac_f32_e32 v68, 0x32a5705f, v66
	v_sub_f32_e32 v67, v67, v69
	v_add_f32_e32 v67, v67, v68
	v_exp_f32_e32 v67, v67
	v_cvt_i32_f32_e32 v68, v69
	v_cmp_ngt_f32_e32 vcc, s65, v66
	s_mov_b64 s[2:3], 0xa000a80
	v_lshl_add_u64 v[20:21], v[18:19], 0, s[2:3]
	v_ldexp_f32 v67, v67, v68
	v_cndmask_b32_e32 v67, 0, v67, vcc
	v_cmp_nlt_f32_e32 vcc, s89, v66
	s_nop 1
	v_cndmask_b32_e32 v66, v177, v67, vcc
	v_pk_mul_f32 v[22:23], v[66:67], v[22:23] op_sel_hi:[0,1]
	v_cvt_pk_bf16_f32 v22, v22, v23
	global_store_dword v[20:21], v22, off
	s_waitcnt vmcnt(29)
	v_lshlrev_b32_e32 v66, 16, v65
	v_and_b32_e32 v22, 0xffff0000, v65
	ds_bpermute_b32 v65, v26, v66
	ds_bpermute_b32 v23, v26, v22
	s_waitcnt lgkmcnt(0)
	v_mul_f32_e32 v20, v84, v66
	v_mul_f32_e32 v21, v85, v22
	v_fmac_f32_e32 v20, v86, v65
	v_fmac_f32_e32 v21, v87, v23
	s_waitcnt lgkmcnt(1)
	v_add_u32_e32 v65, 1, v38
	v_cvt_f32_i32_e32 v65, v65
	s_mov_b64 s[2:3], 0xa000b80
	v_lshl_add_u64 v[22:23], v[18:19], 0, s[2:3]
	v_mul_f32_e32 v66, v31, v65
	v_mul_f32_e32 v67, 0x3fb8aa3b, v66
	v_fma_f32 v68, v66, s64, -v67
	v_rndne_f32_e32 v69, v67
	v_fmac_f32_e32 v68, 0x32a5705f, v66
	v_sub_f32_e32 v67, v67, v69
	v_add_f32_e32 v67, v67, v68
	v_exp_f32_e32 v67, v67
	v_cvt_i32_f32_e32 v68, v69
	v_cmp_ngt_f32_e32 vcc, s65, v66
	v_ldexp_f32 v67, v67, v68
	s_nop 0
	v_cndmask_b32_e32 v67, 0, v67, vcc
	v_cmp_nlt_f32_e32 vcc, s89, v66
	s_nop 1
	v_cndmask_b32_e32 v66, v177, v67, vcc
	v_mul_f32_e32 v66, 0x3e000000, v66
	v_pk_mul_f32 v[20:21], v[66:67], v[20:21] op_sel_hi:[0,1]
	v_cvt_pk_bf16_f32 v20, v20, v21
	global_store_dword v[22:23], v20, off
	s_waitcnt vmcnt(29)
	v_lshlrev_b32_e32 v66, 16, v64
	v_and_b32_e32 v20, 0xffff0000, v64
	ds_bpermute_b32 v64, v26, v66
	ds_bpermute_b32 v21, v26, v20
	s_waitcnt lgkmcnt(0)
	v_mul_f32_e32 v22, v84, v66
	v_mul_f32_e32 v23, v85, v20
	v_fmac_f32_e32 v22, v86, v64
	v_fmac_f32_e32 v23, v87, v21
	s_waitcnt lgkmcnt(1)
	v_mul_f32_e32 v64, v32, v65
	v_mul_f32_e32 v65, 0x3fb8aa3b, v64
	v_fma_f32 v66, v64, s64, -v65
	v_rndne_f32_e32 v67, v65
	v_fmac_f32_e32 v66, 0x32a5705f, v64
	v_sub_f32_e32 v65, v65, v67
	v_add_f32_e32 v65, v65, v66
	v_exp_f32_e32 v65, v65
	v_cvt_i32_f32_e32 v66, v67
	v_cmp_ngt_f32_e32 vcc, s65, v64
	s_mov_b64 s[2:3], 0xa000c80
	v_lshl_add_u64 v[20:21], v[18:19], 0, s[2:3]
	v_ldexp_f32 v65, v65, v66
	v_cndmask_b32_e32 v65, 0, v65, vcc
	v_cmp_nlt_f32_e32 vcc, s89, v64
	s_nop 1
	v_cndmask_b32_e32 v64, v177, v65, vcc
	v_mul_f32_e32 v64, 0x3e000000, v64
	v_pk_mul_f32 v[22:23], v[64:65], v[22:23] op_sel_hi:[0,1]
	v_cvt_pk_bf16_f32 v22, v22, v23
	global_store_dword v[20:21], v22, off
	s_waitcnt vmcnt(29)
	v_lshlrev_b32_e32 v20, 16, v54
	v_and_b32_e32 v21, 0xffff0000, v54
	v_mul_f32_e32 v22, v20, v20
	v_fmac_f32_e32 v22, v21, v21
	s_nop 1
	v_add_f32_dpp v22, v22, v22 row_ror:8 row_mask:0xf bank_mask:0xf
	s_nop 1
	v_add_f32_dpp v22, v22, v22 row_ror:4 row_mask:0xf bank_mask:0xf
	s_nop 1
	v_add_f32_dpp v22, v22, v22 quad_perm:[2,3,0,1] row_mask:0xf bank_mask:0xf
	s_nop 1
	v_add_f32_dpp v22, v22, v22 quad_perm:[1,0,3,2] row_mask:0xf bank_mask:0xf
	v_fmamk_f32 v22, v22, 0x3d000000, v170
	v_rsq_f32_e32 v22, v22
	s_nop 0
	v_pk_mul_f32 v[22:23], v[6:7], v[22:23] op_sel_hi:[1,0]
	s_nop 0
	v_pk_mul_f32 v[22:23], v[22:23], v[20:21]
	ds_bpermute_b32 v20, v29, v22
	ds_bpermute_b32 v21, v29, v23
	v_add_u32_e32 v54, 0, v40
	s_waitcnt lgkmcnt(0)
	v_mul_f32_e32 v22, v88, v22
	v_mul_f32_e32 v23, v89, v23
	v_fmac_f32_e32 v22, v90, v20
	v_fmac_f32_e32 v23, v91, v21
	s_mov_b64 s[2:3], 0xa001180
	v_lshl_add_u64 v[20:21], v[18:19], 0, s[2:3]
	s_mov_b32 s2, 0x3e8293ee
	v_mul_f32_e32 v22, s2, v22
	v_mul_f32_e32 v23, s2, v23
	v_cvt_pk_bf16_f32 v22, v22, v23
	global_store_dword v[20:21], v22, off
	s_waitcnt vmcnt(29)
	v_lshlrev_b32_e32 v20, 16, v63
	v_and_b32_e32 v21, 0xffff0000, v63
	v_mul_f32_e32 v22, v20, v20
	v_fmac_f32_e32 v22, v21, v21
	s_nop 1
	v_add_f32_dpp v22, v22, v22 row_ror:8 row_mask:0xf bank_mask:0xf
	s_nop 1
	v_add_f32_dpp v22, v22, v22 row_ror:4 row_mask:0xf bank_mask:0xf
	s_nop 1
	v_add_f32_dpp v22, v22, v22 quad_perm:[2,3,0,1] row_mask:0xf bank_mask:0xf
	s_nop 1
	v_add_f32_dpp v22, v22, v22 quad_perm:[1,0,3,2] row_mask:0xf bank_mask:0xf
	v_fmamk_f32 v22, v22, 0x3d000000, v170
	v_rsq_f32_e32 v22, v22
	s_nop 0
	v_pk_mul_f32 v[22:23], v[6:7], v[22:23] op_sel_hi:[1,0]
	s_nop 0
	v_pk_mul_f32 v[22:23], v[22:23], v[20:21]
	ds_bpermute_b32 v20, v29, v22
	ds_bpermute_b32 v21, v29, v23
	s_waitcnt lgkmcnt(0)
; #define LAS __attribute__((address_space(3)))
; DI unsigned pk2(float lo, float hi) { f32x2 x = {lo, hi}; return __builtin_bit_cast(unsigned, __builtin_convertvector(x, bf16x2_t)); }
; DI float sum16(float v) { v += __shfl_xor(v, 8); v += __shfl_xor(v, 4); v += __shfl_xor(v, 2); v += __shfl_xor(v, 1); return v; }
; DI float sum32(float v) { v += __shfl_xor(v, 16); return sum16(v); }
; DI float sum64(float v) { v += __shfl_xor(v, 32); return sum32(v); }
; DI f32x2 unpk(unsigned w) { f32x2 r = {bflo(w), bfhi(w)}; return r; }
; DI void post_unit(const Params& p, int l, int unit, LAS unsigned char* lds) {
;     ...
;     for (int s = 0; s < 16; ++s) {
;       f32x2 x = unpk(raw2[hf][s]); u16* pp = row + segcol[s] + 2 * lane;
;       if (s < 2) {
;         const float rs = rsqrtf(sum32(x[0] * x[0] + x[1] * x[1]) * (1.0f / 64.0f) + EPS);
;         x[0] *= rs * qna[2 * hl]; x[1] *= rs * qna[2 * hl + 1]; rope2<4>(x, hl, cs16 + t * 8);
;         x *= LOG2E * 0.125f; *(unsigned*)pp = pk2(x[0], x[1]);
;       } else if (s == 2) {
;         const float rs = rsqrtf(sum64(x[0] * x[0] + x[1] * x[1]) * (1.0f / 128.0f) + EPS);
;         *(LAS unsigned*)(At + t * 272 + lane * 4) = pk2(x[0] * rs, x[1] * rs);
;     ...
;       } else {
;         const float* gn = (s < 14) ? qnc : knc;
;         const float rs = rsqrtf(sum16(x[0] * x[0] + x[1] * x[1]) * (1.0f / 32.0f) + EPS);
;         x[0] *= rs * gn[2 * hl16]; x[1] *= rs * gn[2 * hl16 + 1]; rope2<2>(x, hl16, cs8 + t * 4);
;         if (s < 14) x *= LOG2E * 0.17677669529663687f;
;         *(unsigned*)pp = pk2(x[0], x[1]);
	v_mul_f32_e32 v22, v88, v22
	v_mul_f32_e32 v23, v89, v23
	v_fmac_f32_e32 v22, v90, v20
	v_fmac_f32_e32 v23, v91, v21
	s_mov_b64 s[2:3], 0xa001280
	v_lshl_add_u64 v[20:21], v[18:19], 0, s[2:3]
	s_mov_b32 s2, 0x3e8293ee
	v_mul_f32_e32 v22, s2, v22
	v_mul_f32_e32 v23, s2, v23
	v_cvt_pk_bf16_f32 v22, v22, v23
	global_store_dword v[20:21], v22, off
	s_waitcnt vmcnt(29)
	v_lshlrev_b32_e32 v20, 16, v62
	v_and_b32_e32 v21, 0xffff0000, v62
	v_mul_f32_e32 v22, v20, v20
	v_fmac_f32_e32 v22, v21, v21
	s_nop 1
	v_add_f32_dpp v22, v22, v22 row_ror:8 row_mask:0xf bank_mask:0xf
	s_nop 1
	v_add_f32_dpp v22, v22, v22 row_ror:4 row_mask:0xf bank_mask:0xf
	s_nop 1
	v_add_f32_dpp v22, v22, v22 quad_perm:[2,3,0,1] row_mask:0xf bank_mask:0xf
	s_nop 1
	v_add_f32_dpp v22, v22, v22 quad_perm:[1,0,3,2] row_mask:0xf bank_mask:0xf
	v_fmamk_f32 v22, v22, 0x3d000000, v170
	v_rsq_f32_e32 v22, v22
	s_nop 0
	v_pk_mul_f32 v[22:23], v[8:9], v[22:23] op_sel_hi:[1,0]
	s_nop 0
	v_pk_mul_f32 v[22:23], v[22:23], v[20:21]
	ds_bpermute_b32 v20, v29, v22
	ds_bpermute_b32 v21, v29, v23
	s_waitcnt lgkmcnt(0)
	v_mul_f32_e32 v22, v88, v22
	v_mul_f32_e32 v23, v89, v23
	v_fmac_f32_e32 v22, v90, v20
	v_fmac_f32_e32 v23, v91, v21
	s_mov_b64 s[2:3], 0xa001380
	v_lshl_add_u64 v[20:21], v[18:19], 0, s[2:3]
	v_cvt_pk_bf16_f32 v22, v22, v23
	global_store_dword v[20:21], v22, off
	s_waitcnt vmcnt(29)
	v_lshlrev_b32_e32 v20, 16, v61
	v_and_b32_e32 v21, 0xffff0000, v61
	v_mul_f32_e32 v22, v20, v20
	v_fmac_f32_e32 v22, v21, v21
	s_nop 1
	v_add_f32_dpp v22, v22, v22 row_ror:8 row_mask:0xf bank_mask:0xf
	s_nop 1
	v_add_f32_dpp v22, v22, v22 row_ror:4 row_mask:0xf bank_mask:0xf
	s_nop 1
	v_add_f32_dpp v22, v22, v22 quad_perm:[2,3,0,1] row_mask:0xf bank_mask:0xf
	s_nop 1
	v_add_f32_dpp v22, v22, v22 quad_perm:[1,0,3,2] row_mask:0xf bank_mask:0xf
	v_fmamk_f32 v22, v22, 0x3d000000, v170
	v_rsq_f32_e32 v22, v22
	s_nop 0
	v_pk_mul_f32 v[22:23], v[8:9], v[22:23] op_sel_hi:[1,0]
	s_nop 0
	v_pk_mul_f32 v[22:23], v[22:23], v[20:21]
	ds_bpermute_b32 v20, v29, v22
	ds_bpermute_b32 v21, v29, v23
	s_waitcnt lgkmcnt(0)
	v_mul_f32_e32 v22, v88, v22
	v_mul_f32_e32 v23, v89, v23
	v_fmac_f32_e32 v22, v90, v20
	v_fmac_f32_e32 v23, v91, v21
	s_mov_b64 s[2:3], 0xa001480
	v_lshl_add_u64 v[18:19], v[18:19], 0, s[2:3]
	s_waitcnt lgkmcnt(1)
	v_cvt_pk_bf16_f32 v20, v22, v23
	global_store_dword v[18:19], v20, off
	s_waitcnt vmcnt(29)
	v_and_b32_e32 v19, 0xffff0000, v60
	v_lshlrev_b32_e32 v18, 16, v60
	v_mul_f32_e32 v20, v18, v18
	v_fmac_f32_e32 v20, v19, v19
	v_mov_b32_e32 v21, v20
	s_nop 1
	v_permlane16_swap_b32_e32 v20, v21
	v_add_f32_e32 v20, v20, v21
	s_nop 1
	v_add_f32_dpp v20, v20, v20 row_ror:8 row_mask:0xf bank_mask:0xf
	s_nop 1
	v_add_f32_dpp v20, v20, v20 row_ror:4 row_mask:0xf bank_mask:0xf
	s_nop 1
	v_add_f32_dpp v20, v20, v20 quad_perm:[2,3,0,1] row_mask:0xf bank_mask:0xf
	s_nop 1
	v_add_f32_dpp v20, v20, v20 quad_perm:[1,0,3,2] row_mask:0xf bank_mask:0xf
	v_fmamk_f32 v20, v20, 0x3c800000, v170
	v_rsq_f32_e32 v20, v20
	s_nop 0
	v_mul_f32_e32 v21, v5, v20
	v_mul_f32_e32 v20, v4, v20
	v_mul_f32_e32 v20, v20, v18
	v_mul_f32_e32 v21, v21, v19
	ds_bpermute_b32 v18, v28, v20
	ds_bpermute_b32 v19, v28, v21
	s_waitcnt lgkmcnt(0)
	v_mul_f32_e32 v20, v92, v20
	v_mul_f32_e32 v21, v93, v21
	v_fmac_f32_e32 v20, v94, v18
	v_fmac_f32_e32 v21, v95, v19
	s_mov_b32 s2, 0x3e38aa3b
	v_lshl_add_u64 v[18:19], v[14:15], 0, v[0:1]
	v_mul_f32_e32 v20, s2, v20
	v_mul_f32_e32 v21, s2, v21
	v_cvt_pk_bf16_f32 v22, v20, v21
	v_add_co_u32_e32 v20, vcc, 0xa002000, v18
	s_nop 1
	v_addc_co_u32_e32 v21, vcc, 0, v19, vcc
	global_store_dword v[20:21], v22, off offset:512
	s_waitcnt vmcnt(29)
	v_and_b32_e32 v21, 0xffff0000, v57
	v_lshlrev_b32_e32 v20, 16, v57
	v_mul_f32_e32 v22, v20, v20
	v_fmac_f32_e32 v22, v21, v21
	v_mov_b32_e32 v23, v22
	s_nop 1
	v_permlane16_swap_b32_e32 v22, v23
	v_add_f32_e32 v22, v22, v23
	s_nop 1
	v_add_f32_dpp v22, v22, v22 row_ror:8 row_mask:0xf bank_mask:0xf
	s_nop 1
	v_add_f32_dpp v22, v22, v22 row_ror:4 row_mask:0xf bank_mask:0xf
	s_nop 1
	v_add_f32_dpp v22, v22, v22 quad_perm:[2,3,0,1] row_mask:0xf bank_mask:0xf
	s_nop 1
	v_add_f32_dpp v22, v22, v22 quad_perm:[1,0,3,2] row_mask:0xf bank_mask:0xf
	v_fmamk_f32 v22, v22, 0x3c800000, v170
	v_rsq_f32_e32 v22, v22
	s_nop 0
	v_mul_f32_e32 v23, v5, v22
	v_mul_f32_e32 v22, v4, v22
	v_mul_f32_e32 v22, v22, v20
	v_mul_f32_e32 v23, v23, v21
	ds_bpermute_b32 v20, v28, v22
	ds_bpermute_b32 v21, v28, v23
	s_waitcnt lgkmcnt(0)
	v_mul_f32_e32 v22, v92, v22
	v_mul_f32_e32 v23, v93, v23
	v_fmac_f32_e32 v22, v94, v20
	v_fmac_f32_e32 v23, v95, v21
	s_mov_b32 s2, 0x3e38aa3b
	v_pk_mul_f32 v[20:21], v[22:23], s[2:3] op_sel_hi:[1,0]
	s_nop 0
	v_cvt_pk_bf16_f32 v22, v20, v21
	v_add_co_u32_e32 v20, vcc, 0xa002000, v18
	s_nop 1
	v_addc_co_u32_e32 v21, vcc, 0, v19, vcc
	global_store_dword v[20:21], v22, off offset:768
	s_waitcnt vmcnt(29)
	v_lshlrev_b32_e32 v20, 16, v55
	v_and_b32_e32 v21, 0xffff0000, v55
	v_mul_f32_e32 v22, v20, v20
	v_fmac_f32_e32 v22, v21, v21
	v_mov_b32_e32 v23, v22
	s_nop 1
	v_permlane32_swap_b32_e32 v22, v23
	v_add_f32_e32 v22, v22, v23
	v_mov_b32_e32 v23, v22
	s_nop 1
	v_permlane16_swap_b32_e32 v22, v23
	v_add_f32_e32 v22, v22, v23
	s_nop 1
	v_add_f32_dpp v22, v22, v22 row_ror:8 row_mask:0xf bank_mask:0xf
	s_nop 1
	v_add_f32_dpp v22, v22, v22 row_ror:4 row_mask:0xf bank_mask:0xf
	s_nop 1
	v_add_f32_dpp v22, v22, v22 quad_perm:[2,3,0,1] row_mask:0xf bank_mask:0xf
	s_nop 1
	v_add_f32_dpp v22, v22, v22 quad_perm:[1,0,3,2] row_mask:0xf bank_mask:0xf
	v_fmamk_f32 v22, v22, 0x3c000000, v170
	v_rsq_f32_e32 v22, v22
	s_nop 0
	v_pk_mul_f32 v[20:21], v[22:23], v[20:21] op_sel_hi:[0,1]
	v_cvt_pk_bf16_f32 v20, v20, v21
	ds_write_b32 v59, v20 offset:272
	s_waitcnt vmcnt(28)
	v_lshlrev_b32_e32 v20, 16, v53
	v_and_b32_e32 v21, 0xffff0000, v53
	ds_bpermute_b32 v53, v28, v20
	ds_bpermute_b32 v23, v28, v21
	s_waitcnt lgkmcnt(0)
	v_mul_f32_e32 v20, v92, v20
	v_mul_f32_e32 v21, v93, v21
	v_fmac_f32_e32 v20, v94, v53
	v_fmac_f32_e32 v21, v95, v23
	v_cvt_pk_bf16_f32 v22, v20, v21
	v_add_co_u32_e32 v20, vcc, 0xa002000, v18
	s_nop 1
	v_addc_co_u32_e32 v21, vcc, 0, v19, vcc
	global_store_dword v[20:21], v22, off offset:1280
	s_waitcnt vmcnt(28)
	v_lshlrev_b32_e32 v20, 16, v52
	v_and_b32_e32 v21, 0xffff0000, v52
	ds_bpermute_b32 v52, v28, v20
	s_waitcnt lgkmcnt(1)
	ds_bpermute_b32 v23, v28, v21
	s_and_saveexec_b64 s[2:3], s[12:13]
	s_xor_b64 s[18:19], exec, s[2:3]
	s_cbranch_execz .LBB0_254
	s_and_saveexec_b64 s[30:31], s[14:15]
	s_cbranch_execz .LBB0_253
	v_mov_b32_e32 v22, v21
	s_waitcnt lgkmcnt(0)
	v_mul_f32_e32 v20, v212, v20
	v_mul_f32_e32 v21, v214, v22
	v_fmac_f32_e32 v20, v213, v52
	v_fmac_f32_e32 v21, v215, v23
